# attention: co-resident workgroups alternate s_setprio per key tile (wave-slot parity xor tile parity) to balance VALU arbitration
# baseline (speedup 1.0000x reference)
.LBB0_337:
	s_andn2_b64 vcc, exec, s[44:45]
	s_cbranch_vccnz .LBB0_447
	s_getreg_b32 s100, hwreg(HW_REG_HW_ID, 0, 4)
	s_and_b32 s100, s100, 1
	v_readlane_b32 s38, v254, 28
	v_readlane_b32 s46, v253, 2
	v_readlane_b32 s39, v254, 29
	v_readlane_b32 s47, v253, 3
	v_mov_b32_e32 v0, v133
	s_andn2_b64 vcc, exec, s[38:39]
	s_cbranch_vccnz .LBB0_384
	v_ashrrev_i32_e32 v4, 3, v0
	v_ashrrev_i32_e32 v5, 31, v4
	s_load_dwordx2 s[44:45], s[46:47], 0xf8
	s_nop 0
	s_load_dwordx2 s[46:47], s[46:47], 0xc0
	v_lshlrev_b64 v[6:7], 8, v[4:5]
	v_lshlrev_b32_e32 v5, 3, v0
	v_and_b32_e32 v8, 56, v5
	v_add_u32_e32 v5, 0x100, v0
	v_ashrrev_i32_e32 v10, 3, v5
	v_bfe_u32 v3, v0, 5, 1
	v_ashrrev_i32_e32 v11, 31, v10
	v_and_b32_e32 v14, 64, v188
	s_waitcnt lgkmcnt(0)
	s_add_u32 s48, s44, 0x22600000
	v_cmp_eq_u32_e32 vcc, 0, v3
	v_lshlrev_b64 v[12:13], 8, v[10:11]
	v_xor_b32_e32 v11, 32, v188
	v_add_u32_e32 v14, 64, v14
	v_ashrrev_i32_e32 v2, 1, v0
	s_addc_u32 s49, s45, 0
	s_movk_i32 s3, 0xffe0
	v_cndmask_b32_e64 v107, 0, 1.0, vcc
	v_and_b32_e32 v5, 7, v0
	v_cmp_lt_i32_e32 vcc, v11, v14
	v_readlane_b32 s38, v254, 60
	v_and_b32_e32 v1, 31, v0
	s_add_u32 s50, s44, 0x31600000
	v_bfi_b32 v106, s3, v2, v0
	v_lshlrev_b32_e32 v2, 3, v3
	v_lshlrev_b32_e32 v9, 4, v5
	s_waitcnt vmcnt(0)
	v_lshlrev_b32_e32 v108, 4, v3
	v_cndmask_b32_e32 v11, v188, v11, vcc
	s_movk_i32 s3, 0x470
	v_readlane_b32 s39, v254, 61
	s_addc_u32 s51, s45, 0
	v_lshlrev_b32_e32 v0, 2, v3
	v_sub_u32_e32 v3, v108, v2
	v_lshlrev_b32_e32 v109, 2, v11
	v_mul_lo_u32 v11, v4, s85
	v_lshlrev_b32_e32 v4, 1, v4
	v_mad_u32_u24 v5, v5, s3, v9
	v_mul_lo_u32 v14, v10, s85
	v_lshlrev_b32_e32 v10, 1, v10
	v_mul_u32_u24_e32 v110, 0x90, v1
	s_lshl_b32 s3, s38, 4
	s_lshl_b32 s52, s38, 17
	v_readlane_b32 s38, v253, 0
	s_mov_b32 s53, s81
	v_or_b32_e32 v111, 0x80, v0
	v_lshlrev_b32_e32 v96, 1, v2
	v_lshlrev_b32_e32 v128, 1, v8
	v_add_u32_e32 v112, v9, v11
	v_add_u32_e32 v113, v5, v4
	v_add_u32_e32 v114, v9, v14
	v_add_u32_e32 v115, v5, v10
	v_add_u32_e32 v116, v3, v110
	v_lshrrev_b32_e32 v168, 6, v133
	v_mul_u32_u24_e32 v166, 0x480, v168
	v_bfe_u32 v168, v133, 3, 3
	v_lshl_add_u32 v166, v168, 6, v166
	v_bfe_u32 v168, v133, 2, 1
	v_mul_u32_u24_e32 v168, 0x240, v168
	v_add_u32_e32 v166, v166, v168
	v_and_b32_e32 v168, 3, v133
	v_lshl_add_u32 v166, v168, 4, v166
	v_bfe_u32 v168, v133, 5, 1
	v_lshlrev_b32_e32 v167, 8, v168
	v_bfe_u32 v168, v133, 2, 2
	v_lshl_add_u32 v167, v168, 6, v167
	v_bfe_u32 v168, v133, 4, 1
	v_lshl_add_u32 v167, v168, 5, v167
	v_and_b32_e32 v168, 3, v133
	v_lshl_add_u32 v167, v168, 3, v167
	v_lshlrev_b32_e32 v98, 1, v0
	v_lshlrev_b64 v[100:101], 1, v[6:7]
	v_lshlrev_b64 v[102:103], 1, v[12:13]
	s_mov_b32 s31, s38
	v_readlane_b32 s39, v253, 1
	s_branch .LBB0_341

.LBB0_379:
	s_add_i32 s101, s96, s100
	s_and_b32 s101, s101, 1
	s_cmp_eq_u32 s101, 1
	s_cbranch_scc1 .Lattn_p1
	s_setprio 0
	s_branch .Lattn_p2
.Lattn_p1:
	s_setprio 1

.LBB0_384:
	s_setprio 0
	s_add_i32 s31, s30, 2
	s_cmp_ge_i32 s31, s71
	s_cbranch_scc1 .LBB0_447
	s_cmp_lg_u32 s2, s70
	s_mov_b64 s[44:45], -1
	s_cbranch_scc0 .LBB0_435
	s_waitcnt vmcnt(0)
	s_barrier
	s_mov_b64 s[44:45], exec
	v_readlane_b32 s2, v253, 6
	v_readlane_b32 s3, v253, 7
	s_and_b64 s[2:3], s[44:45], s[2:3]
	s_mov_b64 exec, s[2:3]
	s_cbranch_execz .LBB0_434
	v_mov_b32_e32 v0, 0x12000
	s_waitcnt vmcnt(0) expcnt(0) lgkmcnt(0)
	ds_read_b32 v2, v0
	ds_read_b32 v0, v178
	s_waitcnt lgkmcnt(1)
	v_cmp_ne_u32_e32 vcc, 0, v2
	s_cbranch_vccnz .LBB0_402
	s_mov_b32 s2, 1
	s_branch .LBB0_390
